# v32: v30 + GLA-final k/q loads: one wave-level validity test and stepped base address per head instead of 16 per-token blocks
# speedup vs baseline: 1.0005x; 1.0005x over previous
; template <bool FINAL>
; DI void gla_unit(KA a, int l, int item, LAS unsigned char* lds) {
;     ...
;     for (int hh = 0; hh < 2; ++hh) {
;         const int hd = 2 * hp + hh;
; #pragma unroll
;         for (int jj = 0; jj < 8; ++jj) {
;             const int t = 8 * tg + jj; kraw[hh][jj] = 0u; qraw[hh][jj] = 0u;
;             if (t < nvalid) { kraw[hh][jj] = U[(size_t)(row0 + t) * UN + U_K + hd * 64 + dk]; if (FINAL) qraw[hh][jj] = U[(size_t)(row0 + t) * UN + U_Q + hd * 64 + dk]; }
;         }
;         v0[hh] = (u32x4){0u, 0u, 0u, 0u}; v1[hh] = v0[hh]; g0[hh] = v0[hh]; g1[hh] = v0[hh];
;         if (vj < nvalid) {
;             const u32x4* vp = (const u32x4*)(U + (size_t)(row0 + vj) * UN + U_V + hd * 128 + vdvc); v0[hh] = vp[0]; v1[hh] = vp[1];
;             if (FINAL) { const u32x4* gp = (const u32x4*)(U + (size_t)(row0 + vj) * UN + U_GO + hd * 128 + vdvc); g0[hh] = gp[0]; g1[hh] = gp[1]; }
;         }
.LBB0_796:
	v_mov_b32_e32 v123, v212
	s_load_dwordx2 s[28:29], s[2:3], 0xd8
	s_and_b32 s21, s62, 1
	v_readfirstlane_b32 s44, v123
	s_lshl_b32 s54, s21, 7
	s_ashr_i32 s43, s44, 6
	s_waitcnt lgkmcnt(0)
	s_add_u32 s30, s28, 0x5000000
	s_addc_u32 s31, s29, 0
	s_lshl_b32 s53, s43, 3
	v_and_b32_e32 v85, 63, v123
	s_or_b32 s45, s53, 1
	s_cmp_lt_i32 s53, s0
	s_cselect_b64 s[6:7], -1, 0
	v_mov_b32_e32 v139, 0
	v_mov_b32_e32 v137, 0
	v_mov_b32_e32 v134, 0
	v_mov_b32_e32 v133, 0
	v_mov_b32_e32 v130, 0
	v_mov_b32_e32 v129, 0
	v_mov_b32_e32 v127, 0
	v_mov_b32_e32 v126, 0
	v_mov_b32_e32 v140, 0
	v_mov_b32_e32 v136, 0
	v_mov_b32_e32 v138, 0
	v_mov_b32_e32 v132, 0
	v_mov_b32_e32 v135, 0
	v_mov_b32_e32 v128, 0
	v_mov_b32_e32 v131, 0
	v_mov_b32_e32 v125, 0
	s_cbranch_scc0 .Lgkq0_skip
	s_add_i32 s8, s53, s46
	s_mul_hi_i32 s9, s8, 0x1600
	s_mulk_i32 s8, 0x1600
	s_add_u32 s8, s30, s8
	s_addc_u32 s9, s31, s9
	s_lshl_b32 s12, s54, 1
	s_add_u32 s8, s8, s12
	s_addc_u32 s9, s9, 0
	v_lshlrev_b32_e32 v0, 1, v85
	global_load_short_d16_hi v139, v0, s[8:9] offset:2560
	s_nop 0
	global_load_short_d16_hi v140, v0, s[8:9] offset:2048
	s_add_u32 s8, s8, 0x1600
	s_addc_u32 s9, s9, 0
	global_load_short_d16_hi v137, v0, s[8:9] offset:2560
	s_nop 0
	global_load_short_d16_hi v136, v0, s[8:9] offset:2048
	s_add_u32 s8, s8, 0x1600
	s_addc_u32 s9, s9, 0
	global_load_short_d16_hi v134, v0, s[8:9] offset:2560
	s_nop 0
	global_load_short_d16_hi v138, v0, s[8:9] offset:2048
	s_add_u32 s8, s8, 0x1600
	s_addc_u32 s9, s9, 0
	global_load_short_d16_hi v133, v0, s[8:9] offset:2560
	s_nop 0
	global_load_short_d16_hi v132, v0, s[8:9] offset:2048
	s_add_u32 s8, s8, 0x1600
	s_addc_u32 s9, s9, 0
	global_load_short_d16_hi v130, v0, s[8:9] offset:2560
	s_nop 0
	global_load_short_d16_hi v135, v0, s[8:9] offset:2048
	s_add_u32 s8, s8, 0x1600
	s_addc_u32 s9, s9, 0
	global_load_short_d16_hi v129, v0, s[8:9] offset:2560
	s_nop 0
	global_load_short_d16_hi v128, v0, s[8:9] offset:2048
	s_add_u32 s8, s8, 0x1600
	s_addc_u32 s9, s9, 0
	global_load_short_d16_hi v127, v0, s[8:9] offset:2560
	s_nop 0
	global_load_short_d16_hi v131, v0, s[8:9] offset:2048
	s_add_u32 s8, s8, 0x1600
	s_addc_u32 s9, s9, 0
	global_load_short_d16_hi v126, v0, s[8:9] offset:2560
	s_nop 0
	global_load_short_d16_hi v125, v0, s[8:9] offset:2048
.Lgkq0_skip:
.LBB0_812:
	v_ashrrev_i32_e32 v122, 3, v123
	v_lshlrev_b32_e32 v0, 4, v123
	v_and_b32_e32 v167, 0x70, v0
	v_add_u32_e32 v84, s46, v122
	v_mov_b64_e32 v[0:1], s[30:31]
	v_mad_i64_i32 v[0:1], s[18:19], v84, s64, v[0:1]
	v_lshlrev_b32_e32 v144, 1, v167
	v_lshl_add_u64 v[32:33], v[0:1], 0, v[144:145]
	s_mov_b64 s[18:19], 0x1000
	v_cmp_gt_i32_e64 s[8:9], s0, v122
	v_lshl_add_u64 v[34:35], v[32:33], 0, s[18:19]
	s_lshl_b32 s42, s21, 8
	v_mov_b32_e32 v0, 0
	v_mov_b32_e32 v36, 0
	v_mov_b32_e32 v37, 0
	v_mov_b32_e32 v38, 0
	v_mov_b32_e32 v39, 0
	v_mov_b32_e32 v40, 0
	v_mov_b32_e32 v41, 0
	v_mov_b32_e32 v42, 0
	v_mov_b32_e32 v43, 0
	v_mov_b32_e32 v1, 0
	v_mov_b32_e32 v2, 0
	v_mov_b32_e32 v3, 0
	v_mov_b32_e32 v4, 0
	v_mov_b32_e32 v5, 0
	v_mov_b32_e32 v6, 0
	v_mov_b32_e32 v7, 0
	s_and_saveexec_b64 s[18:19], s[8:9]
	s_cbranch_execz .LBB0_814
	s_lshl_b32 s0, s42, 1
	v_lshl_add_u64 v[0:1], v[32:33], 0, s[0:1]
	v_lshl_add_u64 v[8:9], v[34:35], 0, s[0:1]
	global_load_dwordx4 v[4:7], v[0:1], off offset:3072
	s_nop 0
	global_load_dwordx4 v[0:3], v[0:1], off offset:3088
	s_nop 0
	global_load_dwordx4 v[36:39], v[8:9], off offset:16
	global_load_dwordx4 v[40:43], v[8:9], off

; template <bool FINAL>
; DI void gla_unit(KA a, int l, int item, LAS unsigned char* lds) {
;     ...
;         for (int jj = 0; jj < 8; ++jj) {
;             const int t = 8 * tg + jj; kraw[hh][jj] = 0u; qraw[hh][jj] = 0u;
;             if (t < nvalid) { kraw[hh][jj] = U[(size_t)(row0 + t) * UN + U_K + hd * 64 + dk]; if (FINAL) qraw[hh][jj] = U[(size_t)(row0 + t) * UN + U_Q + hd * 64 + dk]; }
;         }
.LBB0_841:
	s_or_b32 s59, s24, 1
	v_cndmask_b32_e64 v24, 0, 1, s[6:7]
	s_lshl_b32 s0, s59, 6
	v_mov_b32_e32 v142, 0
	v_mov_b32_e32 v155, 0
	v_mov_b32_e32 v156, 0
	v_mov_b32_e32 v158, 0
	v_mov_b32_e32 v160, 0
	v_mov_b32_e32 v162, 0
	v_mov_b32_e32 v164, 0
	v_mov_b32_e32 v166, 0
	v_mov_b32_e32 v154, 0
	v_mov_b32_e32 v141, 0
	v_mov_b32_e32 v157, 0
	v_mov_b32_e32 v143, 0
	v_mov_b32_e32 v161, 0
	v_mov_b32_e32 v159, 0
	v_mov_b32_e32 v165, 0
	v_mov_b32_e32 v163, 0
	v_cmp_ne_u32_e64 s[24:25], 1, v24
	s_andn2_b64 vcc, exec, s[6:7]
	s_cbranch_vccnz .LBB0_857
	s_add_i32 s6, s53, s46
	s_mul_hi_i32 s7, s6, 0x1600
	s_mulk_i32 s6, 0x1600
	s_add_u32 s6, s30, s6
	s_addc_u32 s7, s31, s7
	s_lshl_b32 s10, s0, 1
	s_add_u32 s6, s6, s10
	s_addc_u32 s7, s7, 0
	v_lshlrev_b32_e32 v24, 1, v85
	global_load_short_d16_hi v142, v24, s[6:7] offset:2560
	s_nop 0
	global_load_short_d16_hi v154, v24, s[6:7] offset:2048
	s_add_u32 s6, s6, 0x1600
	s_addc_u32 s7, s7, 0
	global_load_short_d16_hi v155, v24, s[6:7] offset:2560
	s_nop 0
	global_load_short_d16_hi v141, v24, s[6:7] offset:2048
	s_add_u32 s6, s6, 0x1600
	s_addc_u32 s7, s7, 0
	global_load_short_d16_hi v156, v24, s[6:7] offset:2560
	s_nop 0
	global_load_short_d16_hi v157, v24, s[6:7] offset:2048
	s_add_u32 s6, s6, 0x1600
	s_addc_u32 s7, s7, 0
	global_load_short_d16_hi v158, v24, s[6:7] offset:2560
	s_nop 0
	global_load_short_d16_hi v143, v24, s[6:7] offset:2048
	s_add_u32 s6, s6, 0x1600
	s_addc_u32 s7, s7, 0
	global_load_short_d16_hi v160, v24, s[6:7] offset:2560
	s_nop 0
	global_load_short_d16_hi v161, v24, s[6:7] offset:2048
	s_add_u32 s6, s6, 0x1600
	s_addc_u32 s7, s7, 0
	global_load_short_d16_hi v162, v24, s[6:7] offset:2560
	s_nop 0
	global_load_short_d16_hi v159, v24, s[6:7] offset:2048
	s_add_u32 s6, s6, 0x1600
	s_addc_u32 s7, s7, 0
	global_load_short_d16_hi v164, v24, s[6:7] offset:2560
	s_nop 0
	global_load_short_d16_hi v165, v24, s[6:7] offset:2048
	s_add_u32 s6, s6, 0x1600
	s_addc_u32 s7, s7, 0
	global_load_short_d16_hi v166, v24, s[6:7] offset:2560
	s_nop 0
	global_load_short_d16_hi v163, v24, s[6:7] offset:2048
